# speedup vs baseline: 1.0065x; 1.0010x over previous
; DI unsigned pk_bf16(float lo, float hi) { f32x2_t v = {lo, hi}; return __builtin_bit_cast(unsigned, __builtin_convertvector(v, bf16x2_t)); }
; #define MFMA32(a, b, c) __builtin_amdgcn_mfma_f32_32x32x16_bf16((a), (b), (c), 0, 0, 0)
; DI void h1_task(const Params& p, int c, int h, char* lds) {
;     ...
;   const u16* it = (const u16*)(p.ws + OFF_IT) + (size_t)(h * 128 + 32 * w + r) * S + c * 64 + 8 * hh;
; #pragma unroll
;   for (int ks = 0; ks < 4; ++ks) {
;     const bf16x8 vb = *(const bf16x8*)(it + 16 * ks);
; #pragma unroll
;     for (int kt = 0; kt < 4; ++kt) {
;       const int kr = 32 * kt + r, ch = (2 * ks + hh) ^ ((kr >> 1) & 7);
;       const bf16x8 ka = *(const bf16x8*)(lds + kr * 128 + ch * 16);
;       acc[kt] = MFMA32(ka, vb, acc[kt]);
;     }
;   }
;   u16* U = (u16*)(p.ws + OFF_U) + ((size_t)((h * 128 + 32 * w + r) * 2) * 256 + c) * 64;
; #pragma unroll
;   for (int kt = 0; kt < 4; ++kt)
; #pragma unroll
;     for (int g4 = 0; g4 < 4; ++g4) {
;       u32x2 o; o[0] = pk_bf16(acc[kt][4 * g4], acc[kt][4 * g4 + 1]); o[1] = pk_bf16(acc[kt][4 * g4 + 2], acc[kt][4 * g4 + 3]);
;       *(u32x2*)(U + (size_t)(kt >> 1) * 16384 + 32 * (kt & 1) + 8 * g4 + 4 * hh) = o;
;     }
.LBB0_793:
	s_or_b64 exec, exec, s[8:9]
	v_and_b32_e32 v4, 31, v26
	v_lshlrev_b32_e32 v2, 5, v27
	v_or3_b32 v79, v2, v1, v4
	v_readlane_b32 s8, v254, 6
	v_lshlrev_b32_e32 v64, 15, v79
	v_readlane_b32 s9, v254, 7
	v_lshrrev_b32_e32 v78, 5, v28
	v_ashrrev_i32_e32 v1, 31, v0
	v_lshl_add_u64 v[2:3], s[8:9], 0, v[64:65]
	v_lshl_add_u64 v[0:1], v[0:1], 1, v[2:3]
	v_lshlrev_b32_e32 v2, 4, v78
	v_mov_b32_e32 v3, v65
	v_lshl_add_u64 v[76:77], v[0:1], 0, v[2:3]
	s_waitcnt lgkmcnt(0)
	s_barrier
	v_lshrrev_b32_e32 v5, 1, v26
	v_lshlrev_b32_e32 v81, 7, v4
	v_bitop3_b32 v4, v78, v5, 7 bitop3:0x78
	v_lshlrev_b32_e32 v4, 4, v4
	v_add3_u32 v8, v67, v4, v81
	ds_read_b128 v[4:7], v8
	v_bfe_u32 v80, v26, 1, 3
	v_bitop3_b32 v72, v78, v80, 2 bitop3:0x36
	v_lshlrev_b32_e32 v72, 4, v72
	v_add3_u32 v82, v67, v72, v81
	ds_read_b128 v[72:75], v82
	v_readlane_b32 s8, v254, 14
	v_readlane_b32 s9, v254, 15
	v_lshlrev_b32_e32 v64, 3, v78
	s_mov_b32 s7, 0x8000
	s_waitcnt lgkmcnt(1)
	v_mfma_f32_32x32x16_bf16 v[48:63], v[4:7], v[96:99], 0
	ds_read_b128 v[4:7], v8 offset:4096
	s_waitcnt lgkmcnt(1)
	v_mfma_f32_32x32x16_bf16 v[48:63], v[72:75], v[100:103], v[48:63]
	ds_read_b128 v[72:75], v82 offset:4096
	s_waitcnt lgkmcnt(1)
	v_mfma_f32_32x32x16_bf16 v[32:47], v[4:7], v[96:99], 0
	ds_read_b128 v[4:7], v8 offset:8192
	s_waitcnt lgkmcnt(1)
	v_mfma_f32_32x32x16_bf16 v[32:47], v[72:75], v[100:103], v[32:47]
	ds_read_b128 v[72:75], v82 offset:8192
	s_waitcnt lgkmcnt(1)
	v_mfma_f32_32x32x16_bf16 v[16:31], v[4:7], v[96:99], 0
	ds_read_b128 v[4:7], v8 offset:12288
	s_waitcnt lgkmcnt(1)
	v_mfma_f32_32x32x16_bf16 v[16:31], v[72:75], v[100:103], v[16:31]
	ds_read_b128 v[72:75], v82 offset:12288
	s_waitcnt lgkmcnt(1)
	v_mfma_f32_32x32x16_bf16 v[0:15], v[4:7], v[96:99], 0
	s_waitcnt lgkmcnt(0)
	v_mfma_f32_32x32x16_bf16 v[0:15], v[72:75], v[100:103], v[0:15]
	v_bitop3_b32 v72, v78, v80, 4 bitop3:0x36
	v_lshlrev_b32_e32 v72, 4, v72
	v_add3_u32 v82, v67, v72, v81
	ds_read_b128 v[72:75], v82
	s_waitcnt lgkmcnt(0)
	v_mfma_f32_32x32x16_bf16 v[48:63], v[72:75], v[104:107], v[48:63]
	ds_read_b128 v[72:75], v82 offset:4096
	s_waitcnt lgkmcnt(0)
	v_mfma_f32_32x32x16_bf16 v[32:47], v[72:75], v[104:107], v[32:47]
	ds_read_b128 v[72:75], v82 offset:8192
	s_waitcnt lgkmcnt(0)
	v_mfma_f32_32x32x16_bf16 v[16:31], v[72:75], v[104:107], v[16:31]
	ds_read_b128 v[72:75], v82 offset:12288
	s_waitcnt lgkmcnt(0)
	v_mfma_f32_32x32x16_bf16 v[0:15], v[72:75], v[104:107], v[0:15]
	v_bitop3_b32 v72, v78, v80, 6 bitop3:0x36
	v_lshlrev_b32_e32 v72, 4, v72
	v_add3_u32 v67, v67, v72, v81
	ds_read_b128 v[72:75], v67
	s_waitcnt lgkmcnt(0)
	v_mfma_f32_32x32x16_bf16 v[48:63], v[72:75], v[108:111], v[48:63]
	ds_read_b128 v[72:75], v67 offset:4096
	s_nop 10
	v_cvt_pk_bf16_f32 v48, v48, v49
	s_waitcnt lgkmcnt(0)
	v_mfma_f32_32x32x16_bf16 v[32:47], v[72:75], v[108:111], v[32:47]
	ds_read_b128 v[72:75], v67 offset:8192
	v_cvt_pk_bf16_f32 v49, v50, v51
	s_waitcnt lgkmcnt(0)
	v_mfma_f32_32x32x16_bf16 v[16:31], v[72:75], v[108:111], v[16:31]
	ds_read_b128 v[72:75], v67 offset:12288
	v_ashrrev_i32_e32 v67, 31, v66
	s_nop 5
	v_cvt_pk_bf16_f32 v32, v32, v33
	v_cvt_pk_bf16_f32 v33, v34, v35
	s_nop 1
	v_cvt_pk_bf16_f32 v35, v18, v19
	s_waitcnt lgkmcnt(0)
	v_mfma_f32_32x32x16_bf16 v[0:15], v[72:75], v[108:111], v[0:15]
	v_lshlrev_b32_e32 v68, 9, v79
	v_mov_b32_e32 v69, v65
	v_lshl_add_u64 v[66:67], v[68:69], 0, v[66:67]
	v_lshlrev_b64 v[66:67], 7, v[66:67]
	v_lshl_add_u64 v[66:67], s[8:9], 0, v[66:67]
	v_lshl_add_u64 v[66:67], v[66:67], 0, v[64:65]
	global_store_dwordx2 v[66:67], v[32:33], off offset:64
	v_cvt_pk_bf16_f32 v32, v36, v37
	v_cvt_pk_bf16_f32 v33, v38, v39
	global_store_dwordx2 v[66:67], v[32:33], off offset:80
	v_cvt_pk_bf16_f32 v32, v40, v41
	v_cvt_pk_bf16_f32 v33, v42, v43
	global_store_dwordx2 v[66:67], v[32:33], off offset:96
	v_cvt_pk_bf16_f32 v32, v44, v45
	v_cvt_pk_bf16_f32 v33, v46, v47
	s_mov_b64 s[8:9], 0x8000
	global_store_dwordx2 v[66:67], v[32:33], off offset:112
	v_lshl_add_u64 v[32:33], v[66:67], 0, s[8:9]
	v_cvt_pk_bf16_f32 v18, v20, v21
	v_cvt_pk_bf16_f32 v19, v22, v23
	v_cvt_pk_bf16_f32 v34, v16, v17
	v_add_co_u32_e32 v16, vcc, s7, v66
	global_store_dwordx2 v[32:33], v[18:19], off offset:16
	v_cvt_pk_bf16_f32 v18, v24, v25
	v_cvt_pk_bf16_f32 v19, v26, v27
	v_addc_co_u32_e32 v17, vcc, 0, v67, vcc
	global_store_dwordx2 v[32:33], v[18:19], off offset:32
	v_cvt_pk_bf16_f32 v18, v28, v29
	v_cvt_pk_bf16_f32 v19, v30, v31
	s_mov_b64 s[8:9], 0x8040
	v_cvt_pk_bf16_f32 v0, v0, v1
	v_cvt_pk_bf16_f32 v1, v2, v3
	global_store_dwordx2 v[66:67], v[48:49], off
	v_cvt_pk_bf16_f32 v48, v52, v53
	v_cvt_pk_bf16_f32 v49, v54, v55
	global_store_dwordx2 v[32:33], v[18:19], off offset:48
	v_lshl_add_u64 v[18:19], v[66:67], 0, s[8:9]
	global_store_dwordx2 v[16:17], v[0:1], off offset:64
	v_cvt_pk_bf16_f32 v0, v4, v5
	v_cvt_pk_bf16_f32 v1, v6, v7
	v_readlane_b32 s8, v255, 7
	v_readlane_b32 s7, v255, 9
	global_store_dwordx2 v[66:67], v[48:49], off offset:16
	v_cvt_pk_bf16_f32 v48, v56, v57
	v_cvt_pk_bf16_f32 v49, v58, v59
	global_store_dwordx2 v[18:19], v[0:1], off offset:16
	v_cvt_pk_bf16_f32 v0, v8, v9
	v_cvt_pk_bf16_f32 v1, v10, v11
	s_add_i32 s3, s3, s8
	s_add_i32 s2, s2, s7
	global_store_dwordx2 v[66:67], v[48:49], off offset:32
	v_cvt_pk_bf16_f32 v48, v60, v61
	v_cvt_pk_bf16_f32 v49, v62, v63
	global_store_dwordx2 v[18:19], v[0:1], off offset:32
	v_cvt_pk_bf16_f32 v0, v12, v13
	v_cvt_pk_bf16_f32 v1, v14, v15
	s_cmpk_gt_i32 s3, 0x1ff
	global_store_dwordx2 v[66:67], v[48:49], off offset:48
	global_store_dwordx2 v[16:17], v[34:35], off
	global_store_dwordx2 v[18:19], v[0:1], off offset:48
	s_barrier
	v_readlane_b32 s9, v255, 8
	s_cbranch_scc1 .LBB0_781
; DI float h2lo(unsigned u) { return (float)__builtin_bit_cast(f16x2_t, u)[0]; }
; DI float h2hi(unsigned u) { return (float)__builtin_bit_cast(f16x2_t, u)[1]; }
; DI int my_tid() { int t = tid_raw(); asm volatile("" : "+v"(t)); return t; }
; DI void hg_prep(const Params& p, int c, int h, float (&b)[16][2], float (&kk)[16][2], float (&bmid)[2], float (&blast)[2], float* xch) {
;   const int tid = my_tid() & 255, kp = tid & 63, seg = tid >> 6;
;   const u16* G = (const u16*)(p.ws + OFF_GH) + (size_t)(c * 64 + seg * 16) * 512 + h * 128 + 2 * kp;
;   unsigned raw[16];
; #pragma unroll
;   for (int i = 0; i < 16; ++i) raw[i] = *(const unsigned*)(G + (size_t)i * 512);
;   float run0 = 0.f, run1 = 0.f;
; #pragma unroll
;   for (int i = 0; i < 16; ++i) {
;     const float g0 = h2lo(raw[i]), g1 = h2hi(raw[i]);
;     run0 += g0; run1 += g1; b[i][0] = run0; b[i][1] = run1;
;     kk[i][0] = 1.0f - __expf(g0); kk[i][1] = 1.0f - __expf(g1);
;   }
; DI void h1_task(const Params& p, int c, int h, char* lds) {
;     ...
;   const u16* it = (const u16*)(p.ws + OFF_IT) + (size_t)(h * 128 + 32 * w + r) * S + c * 64 + 8 * hh;
; #pragma unroll
;   for (int ks = 0; ks < 4; ++ks) {
;     const bf16x8 vb = *(const bf16x8*)(it + 16 * ks);
.LBB0_794:
	s_getreg_b32 s7, hwreg(HW_REG_HW_ID, 0, 6)
	s_lshl_b32 s7, s7, 2
	s_and_b32 s7, s7, 0xfc
	s_add_i32 s7, s7, 0x20040
	v_mov_b32_e32 v0, s7
	ds_read_b32 v0, v0
	v_readlane_b32 s8, v253, 58
	v_readlane_b32 s9, v253, 59
	s_waitcnt lgkmcnt(0)
	v_readfirstlane_b32 s7, v0
	s_nop 1
	v_lshl_or_b32 v0, s7, 6, v214
	s_getreg_b32 s7, hwreg(HW_REG_HW_ID, 0, 6)
	s_lshl_b32 s7, s7, 2
	s_and_b32 s7, s7, 0xfc
	s_add_i32 s7, s7, 0x20040
	v_mov_b32_e32 v1, s7
	ds_read_b32 v1, v1
	v_ashrrev_i32_e32 v3, 8, v0
	v_add_u32_e32 v2, s2, v3
	v_ashrrev_i32_e32 v66, 2, v2
	v_mad_i32_i24 v67, v3, s48, 0
	s_waitcnt lgkmcnt(0)
	v_readfirstlane_b32 s7, v1
	v_lshlrev_b32_e32 v1, 7, v2
	v_and_b32_e32 v1, 0x180, v1
	v_lshl_or_b32 v26, s7, 6, v214
	s_getreg_b32 s7, hwreg(HW_REG_HW_ID, 0, 6)
	s_lshl_b32 s7, s7, 2
	s_and_b32 s7, s7, 0xfc
	s_add_i32 s7, s7, 0x20040
	v_mov_b32_e32 v0, s7
	ds_read_b32 v4, v0
	v_lshlrev_b32_e32 v0, 6, v66
	v_lshlrev_b32_e32 v64, 1, v1
	v_bfe_u32 v27, v26, 6, 2
	v_and_b32_e32 v28, 63, v26
	v_and_b32_e32 v89, 31, v26
	v_lshlrev_b32_e32 v90, 5, v27
	v_readlane_b32 s100, v254, 6
	v_readlane_b32 s101, v254, 7
	v_or3_b32 v89, v90, v1, v89
	v_lshlrev_b32_e32 v90, 15, v89
	v_mov_b32_e32 v91, 0
	v_lshl_add_u64 v[90:91], s[100:101], 0, v[90:91]
	v_mov_b32_e32 v92, v0
	v_ashrrev_i32_e32 v93, 31, v0
	v_lshl_add_u64 v[90:91], v[92:93], 1, v[90:91]
	v_lshrrev_b32_e32 v92, 5, v28
	v_lshlrev_b32_e32 v92, 4, v92
	v_mov_b32_e32 v93, 0
	v_lshl_add_u64 v[90:91], v[90:91], 0, v[92:93]
	global_load_dwordx4 v[96:99], v[90:91], off
	global_load_dwordx4 v[100:103], v[90:91], off offset:32
	global_load_dwordx4 v[104:107], v[90:91], off offset:64
	global_load_dwordx4 v[108:111], v[90:91], off offset:96
	s_waitcnt lgkmcnt(0)
	v_readfirstlane_b32 s7, v4
	s_nop 1
	v_lshl_or_b32 v29, s7, 6, v214
	s_movk_i32 s7, 0x2000
	v_bfe_u32 v88, v29, 6, 2
	v_lshl_or_b32 v4, v88, 4, v0
	v_ashrrev_i32_e32 v5, 31, v4
	v_lshlrev_b64 v[4:5], 10, v[4:5]
	v_and_b32_e32 v81, 63, v29
	v_lshl_add_u64 v[4:5], s[8:9], 0, v[4:5]
	v_lshl_add_u64 v[4:5], v[4:5], 0, v[64:65]
	v_lshlrev_b32_e32 v64, 2, v81
	v_lshl_add_u64 v[4:5], v[4:5], 0, v[64:65]
	v_add_co_u32_e32 v6, vcc, s7, v4
	global_load_dword v10, v[4:5], off
	global_load_dword v11, v[4:5], off offset:1024
	global_load_dword v12, v[4:5], off offset:2048
	global_load_dword v13, v[4:5], off offset:3072
	v_addc_co_u32_e32 v7, vcc, 0, v5, vcc
	s_movk_i32 s7, 0x1000
	v_add_co_u32_e32 v8, vcc, s7, v4
	global_load_dword v16, v[6:7], off offset:-4096
	s_nop 0
	v_addc_co_u32_e32 v9, vcc, 0, v5, vcc
	global_load_dword v17, v[8:9], off offset:1024
	global_load_dword v23, v[8:9], off offset:2048
	global_load_dword v25, v[8:9], off offset:3072
	global_load_dword v31, v[6:7], off
	global_load_dword v33, v[6:7], off offset:1024
	global_load_dword v49, v[6:7], off offset:2048
	global_load_dword v3, v[6:7], off offset:3072
	v_add_co_u32_e32 v4, vcc, s75, v4
	s_waitcnt vmcnt(10)
	v_cvt_f32_f16_e32 v6, v11
	v_addc_co_u32_e32 v5, vcc, 0, v5, vcc
	global_load_dword v64, v[4:5], off
	global_load_dword v74, v[4:5], off offset:1024
	global_load_dword v75, v[4:5], off offset:2048
	global_load_dword v80, v[4:5], off offset:3072
	v_cvt_f32_f16_e32 v4, v10
	v_cvt_f32_f16_sdwa v5, v10 dst_sel:DWORD dst_unused:UNUSED_PAD src0_sel:WORD_1
	v_cvt_f32_f16_sdwa v7, v11 dst_sel:DWORD dst_unused:UNUSED_PAD src0_sel:WORD_1
	s_waitcnt vmcnt(12)
	v_cvt_f32_f16_sdwa v15, v13 dst_sel:DWORD dst_unused:UNUSED_PAD src0_sel:WORD_1
	v_cvt_f32_f16_e32 v8, v12
	v_cvt_f32_f16_sdwa v9, v12 dst_sel:DWORD dst_unused:UNUSED_PAD src0_sel:WORD_1
	s_waitcnt vmcnt(10)
	v_cvt_f32_f16_e32 v20, v17
	v_cvt_f32_f16_sdwa v21, v17 dst_sel:DWORD dst_unused:UNUSED_PAD src0_sel:WORD_1
	s_waitcnt vmcnt(9)
	v_cvt_f32_f16_e32 v22, v23
	v_cvt_f32_f16_sdwa v23, v23 dst_sel:DWORD dst_unused:UNUSED_PAD src0_sel:WORD_1
	s_waitcnt vmcnt(8)
	v_cvt_f32_f16_e32 v24, v25
	v_cvt_f32_f16_sdwa v25, v25 dst_sel:DWORD dst_unused:UNUSED_PAD src0_sel:WORD_1
	s_waitcnt vmcnt(7)
	v_cvt_f32_f16_e32 v30, v31
	v_cvt_f32_f16_e32 v14, v13
	v_cvt_f32_f16_e32 v18, v16
	v_cvt_f32_f16_sdwa v19, v16 dst_sel:DWORD dst_unused:UNUSED_PAD src0_sel:WORD_1
	v_pk_add_f32 v[34:35], v[4:5], 0 op_sel_hi:[1,0]
	v_mul_f32_e32 v11, 0x3fb8aa3b, v7
	v_mul_f32_e32 v42, 0x3fb8aa3b, v15
	v_pk_add_f32 v[38:39], v[34:35], v[6:7]
	v_mul_f32_e32 v10, 0x3fb8aa3b, v6
	v_mul_f32_e32 v13, 0x3fb8aa3b, v9
	v_exp_f32_e32 v17, v11
	v_exp_f32_e32 v11, v42
	v_mul_f32_e32 v6, 0x3fb8aa3b, v20
	v_mul_f32_e32 v7, 0x3fb8aa3b, v21
	v_mul_f32_e32 v47, 0x3fb8aa3b, v23
	v_mul_f32_e32 v48, 0x3fb8aa3b, v24
	v_mul_f32_e32 v50, 0x3fb8aa3b, v25
	v_mul_f32_e32 v51, 0x3fb8aa3b, v30
	v_pk_add_f32 v[42:43], v[38:39], v[8:9]
	v_exp_f32_e32 v37, v10
	v_exp_f32_e32 v10, v13
	v_exp_f32_e32 v45, v6
	v_exp_f32_e32 v13, v7
	v_exp_f32_e32 v6, v47
	v_exp_f32_e32 v47, v48
	v_exp_f32_e32 v7, v50
	v_exp_f32_e32 v48, v51
	v_pk_add_f32 v[50:51], v[42:43], v[14:15]
	v_cvt_f32_f16_sdwa v31, v31 dst_sel:DWORD dst_unused:UNUSED_PAD src0_sel:WORD_1
	v_pk_add_f32 v[52:53], v[50:51], v[18:19]
	s_waitcnt vmcnt(6)
	v_cvt_f32_f16_e32 v32, v33
	v_cvt_f32_f16_sdwa v33, v33 dst_sel:DWORD dst_unused:UNUSED_PAD src0_sel:WORD_1
	v_pk_add_f32 v[54:55], v[52:53], v[20:21]
	v_mul_f32_e32 v12, 0x3fb8aa3b, v8
	v_pk_add_f32 v[56:57], v[54:55], v[22:23]
	s_waitcnt vmcnt(5)
	v_cvt_f32_f16_e32 v8, v49
	v_cvt_f32_f16_sdwa v9, v49 dst_sel:DWORD dst_unused:UNUSED_PAD src0_sel:WORD_1
	v_mul_f32_e32 v41, 0x3fb8aa3b, v14
	v_pk_add_f32 v[58:59], v[56:57], v[24:25]
	s_waitcnt vmcnt(4)
; DI unsigned pk_bf16(float lo, float hi) { f32x2_t v = {lo, hi}; return __builtin_bit_cast(unsigned, __builtin_convertvector(v, bf16x2_t)); }
; DI float h2lo(unsigned u) { return (float)__builtin_bit_cast(f16x2_t, u)[0]; }
; DI float h2hi(unsigned u) { return (float)__builtin_bit_cast(f16x2_t, u)[1]; }
; DI int my_tid() { int t = tid_raw(); asm volatile("" : "+v"(t)); return t; }
; DI void hg_prep(const Params& p, int c, int h, float (&b)[16][2], float (&kk)[16][2], float (&bmid)[2], float (&blast)[2], float* xch) {
;     ...
;   float run0 = 0.f, run1 = 0.f;
; #pragma unroll
;   for (int i = 0; i < 16; ++i) {
;     const float g0 = h2lo(raw[i]), g1 = h2hi(raw[i]);
;     run0 += g0; run1 += g1; b[i][0] = run0; b[i][1] = run1;
;     kk[i][0] = 1.0f - __expf(g0); kk[i][1] = 1.0f - __expf(g1);
;   }
;   f32x2_t* x2 = (f32x2_t*)xch;
;   x2[seg * 64 + kp] = (f32x2_t){run0, run1};
;   __syncthreads();
;   const f32x2_t t0 = x2[kp], t1 = x2[64 + kp], t2 = x2[128 + kp], t3 = x2[192 + kp];
;   f32x2_t off = {0.f, 0.f};
;   if (seg >= 1) off += t0;
;   if (seg >= 2) off += t1;
;   if (seg >= 3) off += t2;
; #pragma unroll
;   for (int i = 0; i < 16; ++i) { b[i][0] += off[0]; b[i][1] += off[1]; }
;   bmid[0] = t0[0] + t1[0]; bmid[1] = t0[1] + t1[1];
;   blast[0] = (t0[0] + t1[0]) + (t2[0] + t3[0]); blast[1] = (t0[1] + t1[1]) + (t2[1] + t3[1]);
;   __syncthreads();
; }
; DI void h1_task(const Params& p, int c, int h, char* lds) {
;   const int tid = my_tid() & 255, lane = tid & 63, w = tid >> 6, r = lane & 31, hh = lane >> 5;
;   float* xch = (float*)(lds + 16384);
;   {
;     const int kp = tid & 63, seg = tid >> 6;
;     float b[16][2], kk[16][2], bmid[2], blast[2];
;     hg_prep(p, c, h, b, kk, bmid, blast, xch);
; #pragma unroll
;     for (int j = 0; j < 2; ++j)
; #pragma unroll
;       for (int q = 0; q < 2; ++q) {
;         u32x4 o;
; #pragma unroll
;         for (int e = 0; e < 4; ++e) {
;           const int i0 = q * 8 + e * 2;
;           o[e] = pk_bf16(kk[i0][j] * __expf(blast[j] - b[i0][j]), kk[i0 + 1][j] * __expf(blast[j] - b[i0 + 1][j]));
;         }
;         const int kq = 2 * kp + j, ch = (seg * 2 + q) ^ ((kq >> 1) & 7);
;         *(u32x4*)(lds + kq * 128 + ch * 16) = o;
	v_cvt_f32_f16_e32 v14, v3
	v_mul_f32_e32 v4, 0x3fb8aa3b, v4
	v_mul_f32_e32 v5, 0x3fb8aa3b, v5
	v_pk_add_f32 v[24:25], v[58:59], v[30:31]
	v_cvt_f32_f16_sdwa v15, v3 dst_sel:DWORD dst_unused:UNUSED_PAD src0_sel:WORD_1
	v_exp_f32_e32 v36, v4
	v_exp_f32_e32 v16, v5
	v_mul_f32_e32 v4, 0x3fb8aa3b, v18
	v_mul_f32_e32 v5, 0x3fb8aa3b, v19
	v_pk_add_f32 v[60:61], v[24:25], v[32:33]
	v_mul_f32_e32 v3, 0x3fb8aa3b, v9
	v_pk_add_f32 v[62:63], v[60:61], v[8:9]
	v_mul_f32_e32 v8, 0x3fb8aa3b, v8
	v_exp_f32_e32 v68, v8
	v_exp_f32_e32 v8, v3
	v_mul_f32_e32 v3, 0x3fb8aa3b, v14
	v_pk_add_f32 v[70:71], v[62:63], v[14:15]
	v_exp_f32_e32 v69, v3
	v_mul_f32_e32 v3, 0x3fb8aa3b, v15
	v_exp_f32_e32 v9, v3
	v_exp_f32_e32 v44, v4
	v_mul_f32_e32 v4, 0x3fb8aa3b, v31
	v_mul_f32_e32 v46, 0x3fb8aa3b, v22
	v_exp_f32_e32 v40, v12
	v_exp_f32_e32 v12, v5
	s_waitcnt vmcnt(3)
	v_cvt_f32_f16_e32 v18, v64
	v_cvt_f32_f16_sdwa v19, v64 dst_sel:DWORD dst_unused:UNUSED_PAD src0_sel:WORD_1
	s_waitcnt vmcnt(2)
	v_cvt_f32_f16_e32 v20, v74
	v_cvt_f32_f16_sdwa v21, v74 dst_sel:DWORD dst_unused:UNUSED_PAD src0_sel:WORD_1
	v_mul_f32_e32 v3, 0x3fb8aa3b, v18
	v_pk_add_f32 v[72:73], v[70:71], v[18:19]
	s_waitcnt vmcnt(1)
	v_cvt_f32_f16_e32 v18, v75
	v_exp_f32_e32 v74, v3
	v_mul_f32_e32 v3, 0x3fb8aa3b, v19
	v_cvt_f32_f16_sdwa v19, v75 dst_sel:DWORD dst_unused:UNUSED_PAD src0_sel:WORD_1
	v_exp_f32_e32 v14, v3
	v_mul_f32_e32 v3, 0x3fb8aa3b, v20
	s_waitcnt vmcnt(0)
	v_cvt_f32_f16_e32 v30, v80
	v_cvt_f32_f16_sdwa v31, v80 dst_sel:DWORD dst_unused:UNUSED_PAD src0_sel:WORD_1
	v_exp_f32_e32 v75, v3
	v_mul_f32_e32 v3, 0x3fb8aa3b, v21
	v_pk_add_f32 v[76:77], v[72:73], v[20:21]
	v_exp_f32_e32 v15, v3
	v_mul_f32_e32 v3, 0x3fb8aa3b, v18
	v_pk_add_f32 v[78:79], v[76:77], v[18:19]
	v_exp_f32_e32 v80, v3
	v_mul_f32_e32 v3, 0x3fb8aa3b, v19
	v_and_b32_e32 v19, 0xff, v29
	v_pk_add_f32 v[82:83], v[78:79], v[30:31]
	v_lshl_add_u32 v19, v19, 3, v67
	v_lshl_add_u32 v29, v81, 3, v67
	ds_write_b64 v19, v[82:83] offset:16384
	s_waitcnt lgkmcnt(0)
	s_barrier
	ds_read2st64_b64 v[20:23], v29 offset0:32 offset1:33
	v_mul_f32_e32 v5, 0x3fb8aa3b, v32
	v_exp_f32_e32 v18, v3
	v_mul_f32_e32 v3, 0x3fb8aa3b, v30
	v_exp_f32_e32 v49, v5
	v_mul_f32_e32 v5, 0x3fb8aa3b, v33
	v_exp_f32_e32 v81, v3
	v_mul_f32_e32 v3, 0x3fb8aa3b, v31
	ds_read2st64_b64 v[30:33], v29 offset0:34 offset1:35
	s_waitcnt lgkmcnt(1)
	v_pk_add_f32 v[84:85], v[20:21], 0 op_sel_hi:[1,0]
	v_cmp_ne_u32_e32 vcc, 0, v88
	v_exp_f32_e32 v41, v41
	v_exp_f32_e32 v46, v46
	v_cndmask_b32_e32 v85, 0, v85, vcc
	v_cndmask_b32_e32 v84, 0, v84, vcc
	v_pk_add_f32 v[86:87], v[22:23], v[84:85]
	v_cmp_lt_u32_e32 vcc, 1, v88
	v_pk_add_f32 v[22:23], v[20:21], v[22:23]
	v_mov_b32_e32 v21, v58
	v_cndmask_b32_e32 v85, v85, v87, vcc
	v_cndmask_b32_e32 v84, v84, v86, vcc
	s_waitcnt lgkmcnt(0)
	v_pk_add_f32 v[86:87], v[30:31], v[84:85]
	v_cmp_eq_u32_e32 vcc, 3, v88
	v_pk_add_f32 v[30:31], v[30:31], v[32:33]
	v_mov_b32_e32 v20, v22
	v_cndmask_b32_e32 v84, v84, v86, vcc
	v_cndmask_b32_e32 v85, v85, v87, vcc
	v_mov_b32_e32 v32, v30
	v_mov_b32_e32 v33, v84
	v_pk_add_f32 v[34:35], v[34:35], v[84:85]
	v_pk_add_f32 v[42:43], v[42:43], v[84:85]
	v_pk_add_f32 v[20:21], v[20:21], v[32:33]
	v_pk_add_f32 v[38:39], v[38:39], v[84:85]
	v_sub_f32_e32 v30, v20, v34
	v_sub_f32_e32 v34, v20, v42
	v_pk_add_f32 v[50:51], v[50:51], v[84:85]
	v_pk_add_f32 v[52:53], v[52:53], v[84:85]
	v_pk_add_f32 v[54:55], v[54:55], v[84:85]
	v_pk_add_f32 v[56:57], v[56:57], v[84:85]
	v_pk_add_f32 v[86:87], v[24:25], v[84:85]
	v_pk_add_f32 v[60:61], v[60:61], v[84:85]
	v_pk_add_f32 v[62:63], v[62:63], v[84:85]
	v_pk_add_f32 v[70:71], v[70:71], v[84:85]
	v_pk_add_f32 v[72:73], v[72:73], v[84:85]
	v_pk_add_f32 v[76:77], v[76:77], v[84:85]
	v_pk_add_f32 v[78:79], v[78:79], v[84:85]
	v_pk_add_f32 v[24:25], v[82:83], v[84:85]
	v_mov_b32_e32 v84, v31
	v_sub_f32_e32 v31, v20, v38
	v_mul_f32_e32 v34, 0x3fb8aa3b, v34
	v_mul_f32_e32 v30, 0x3fb8aa3b, v30
	v_mul_f32_e32 v31, 0x3fb8aa3b, v31
	v_pk_add_f32 v[32:33], v[36:37], 1.0 op_sel_hi:[1,0] neg_lo:[1,0] neg_hi:[1,0]
	v_exp_f32_e32 v36, v34
	v_sub_f32_e32 v34, v20, v50
	v_exp_f32_e32 v30, v30
	v_exp_f32_e32 v31, v31
	v_mul_f32_e32 v34, 0x3fb8aa3b, v34
	v_exp_f32_e32 v37, v34
	v_sub_f32_e32 v34, v20, v56
	v_pk_mul_f32 v[30:31], v[32:33], v[30:31]
	v_pk_add_f32 v[32:33], v[40:41], 1.0 op_sel_hi:[1,0] neg_lo:[1,0] neg_hi:[1,0]
	v_cvt_pk_bf16_f32 v30, v30, v31
	v_pk_mul_f32 v[32:33], v[32:33], v[36:37]
	v_sub_f32_e32 v21, v20, v21
	v_cvt_pk_bf16_f32 v31, v32, v33
	v_sub_f32_e32 v32, v20, v52
	v_sub_f32_e32 v33, v20, v54
	v_mul_f32_e32 v32, 0x3fb8aa3b, v32
	v_mul_f32_e32 v33, 0x3fb8aa3b, v33
	v_exp_f32_e32 v32, v32
	v_exp_f32_e32 v33, v33
	v_mul_f32_e32 v34, 0x3fb8aa3b, v34
	v_mul_f32_e32 v21, 0x3fb8aa3b, v21
	v_exp_f32_e32 v40, v34
	v_exp_f32_e32 v41, v21
	v_pk_add_f32 v[36:37], v[44:45], 1.0 op_sel_hi:[1,0] neg_lo:[1,0] neg_hi:[1,0]
	v_exp_f32_e32 v19, v3
	v_mov_b32_e32 v58, v23
	v_lshlrev_b32_e32 v3, 1, v27
	v_pk_mul_f32 v[32:33], v[36:37], v[32:33]
	v_pk_add_f32 v[36:37], v[46:47], 1.0 op_sel_hi:[1,0] neg_lo:[1,0] neg_hi:[1,0]
	v_pk_add_f32 v[22:23], v[58:59], v[84:85]
	v_lshl_add_u32 v58, v28, 8, v67
	v_pk_mul_f32 v[36:37], v[36:37], v[40:41]
	v_bitop3_b32 v21, v3, v26, 7 bitop3:0x78
	v_cvt_pk_bf16_f32 v32, v32, v33
	v_cvt_pk_bf16_f32 v33, v36, v37
	v_lshl_add_u32 v21, v21, 4, v58
	v_sub_f32_e32 v34, v20, v62
	s_barrier
; DI unsigned pk_bf16(float lo, float hi) { f32x2_t v = {lo, hi}; return __builtin_bit_cast(unsigned, __builtin_convertvector(v, bf16x2_t)); }
; DI void h1_task(const Params& p, int c, int h, char* lds) {
;     ...
;     for (int j = 0; j < 2; ++j)
; #pragma unroll
;       for (int q = 0; q < 2; ++q) {
;         u32x4 o;
; #pragma unroll
;         for (int e = 0; e < 4; ++e) {
;           const int i0 = q * 8 + e * 2;
;           o[e] = pk_bf16(kk[i0][j] * __expf(blast[j] - b[i0][j]), kk[i0 + 1][j] * __expf(blast[j] - b[i0 + 1][j]));
;         }
;         const int kq = 2 * kp + j, ch = (seg * 2 + q) ^ ((kq >> 1) & 7);
;         *(u32x4*)(lds + kq * 128 + ch * 16) = o;
;       }
;     if (seg == 3) *(f32x2_t*)((float*)(p.ws + OFF_DV) + (size_t)(c * 4 + h) * 128 + 2 * kp) = (f32x2_t){__expf(blast[0]), __expf(blast[1])};
	ds_write_b128 v21, v[30:33]
	v_sub_f32_e32 v30, v20, v86
	v_sub_f32_e32 v31, v20, v60
	v_mul_f32_e32 v34, 0x3fb8aa3b, v34
	v_mul_f32_e32 v30, 0x3fb8aa3b, v30
	v_mul_f32_e32 v31, 0x3fb8aa3b, v31
	v_exp_f32_e32 v36, v34
	v_sub_f32_e32 v34, v20, v70
	v_exp_f32_e32 v30, v30
	v_exp_f32_e32 v31, v31
	v_mul_f32_e32 v34, 0x3fb8aa3b, v34
	v_exp_f32_e32 v37, v34
	v_pk_add_f32 v[32:33], v[48:49], 1.0 op_sel_hi:[1,0] neg_lo:[1,0] neg_hi:[1,0]
	v_sub_f32_e32 v34, v20, v78
	v_pk_mul_f32 v[30:31], v[32:33], v[30:31]
	v_pk_add_f32 v[32:33], v[68:69], 1.0 op_sel_hi:[1,0] neg_lo:[1,0] neg_hi:[1,0]
	v_cvt_pk_bf16_f32 v30, v30, v31
	v_pk_mul_f32 v[32:33], v[32:33], v[36:37]
	v_sub_f32_e32 v24, v20, v24
	v_cvt_pk_bf16_f32 v31, v32, v33
	v_sub_f32_e32 v32, v20, v72
	v_sub_f32_e32 v33, v20, v76
	v_mul_f32_e32 v32, 0x3fb8aa3b, v32
	v_mul_f32_e32 v33, 0x3fb8aa3b, v33
	v_exp_f32_e32 v32, v32
	v_exp_f32_e32 v33, v33
	v_mul_f32_e32 v34, 0x3fb8aa3b, v34
	v_mul_f32_e32 v24, 0x3fb8aa3b, v24
	v_exp_f32_e32 v40, v34
	v_exp_f32_e32 v41, v24
	v_pk_add_f32 v[36:37], v[74:75], 1.0 op_sel_hi:[1,0] neg_lo:[1,0] neg_hi:[1,0]
	v_and_b32_e32 v29, 7, v26
	v_pk_mul_f32 v[32:33], v[36:37], v[32:33]
	v_pk_add_f32 v[36:37], v[80:81], 1.0 op_sel_hi:[1,0] neg_lo:[1,0] neg_hi:[1,0]
	v_bitop3_b32 v3, v3, v29, 1 bitop3:0x36
	v_pk_mul_f32 v[36:37], v[36:37], v[40:41]
	v_sub_f32_e32 v24, v22, v35
	v_cvt_pk_bf16_f32 v32, v32, v33
	v_cvt_pk_bf16_f32 v33, v36, v37
	v_lshl_add_u32 v3, v3, 4, v58
	v_mul_f32_e32 v24, 0x3fb8aa3b, v24
	ds_write_b128 v3, v[30:33]
	v_exp_f32_e32 v30, v24
	v_sub_f32_e32 v24, v22, v39
	v_mul_f32_e32 v24, 0x3fb8aa3b, v24
	v_exp_f32_e32 v31, v24
	v_sub_f32_e32 v24, v22, v43
	v_mul_f32_e32 v24, 0x3fb8aa3b, v24
	v_exp_f32_e32 v32, v24
	v_sub_f32_e32 v24, v22, v51
	v_mul_f32_e32 v24, 0x3fb8aa3b, v24
	v_exp_f32_e32 v33, v24
	v_pk_add_f32 v[16:17], v[16:17], 1.0 op_sel_hi:[1,0] neg_lo:[1,0] neg_hi:[1,0]
	v_pk_add_f32 v[10:11], v[10:11], 1.0 op_sel_hi:[1,0] neg_lo:[1,0] neg_hi:[1,0]
	v_pk_mul_f32 v[16:17], v[16:17], v[30:31]
	v_pk_mul_f32 v[10:11], v[10:11], v[32:33]
	v_cvt_pk_bf16_f32 v30, v16, v17
	v_sub_f32_e32 v16, v22, v57
	v_sub_f32_e32 v17, v22, v23
	v_cvt_pk_bf16_f32 v31, v10, v11
	v_sub_f32_e32 v10, v22, v53
	v_sub_f32_e32 v11, v22, v55
	v_mul_f32_e32 v16, 0x3fb8aa3b, v16
	v_mul_f32_e32 v17, 0x3fb8aa3b, v17
	v_mul_f32_e32 v10, 0x3fb8aa3b, v10
	v_mul_f32_e32 v11, 0x3fb8aa3b, v11
	v_exp_f32_e32 v16, v16
	v_exp_f32_e32 v17, v17
	v_exp_f32_e32 v10, v10
	v_exp_f32_e32 v11, v11
	v_pk_add_f32 v[6:7], v[6:7], 1.0 op_sel_hi:[1,0] neg_lo:[1,0] neg_hi:[1,0]
	v_pk_add_f32 v[12:13], v[12:13], 1.0 op_sel_hi:[1,0] neg_lo:[1,0] neg_hi:[1,0]
	v_pk_mul_f32 v[6:7], v[6:7], v[16:17]
	v_pk_mul_f32 v[10:11], v[12:13], v[10:11]
	v_cvt_pk_bf16_f32 v33, v6, v7
	v_sub_f32_e32 v6, v22, v87
	v_sub_f32_e32 v7, v22, v61
	v_exp_f32_e32 v4, v4
	v_exp_f32_e32 v5, v5
	v_cvt_pk_bf16_f32 v32, v10, v11
	v_mul_f32_e32 v6, 0x3fb8aa3b, v6
	v_mul_f32_e32 v7, 0x3fb8aa3b, v7
	v_sub_f32_e32 v10, v22, v63
	v_sub_f32_e32 v11, v22, v71
	v_exp_f32_e32 v6, v6
	v_exp_f32_e32 v7, v7
	v_mul_f32_e32 v10, 0x3fb8aa3b, v10
	v_mul_f32_e32 v11, 0x3fb8aa3b, v11
	v_exp_f32_e32 v10, v10
	v_exp_f32_e32 v11, v11
	v_pk_add_f32 v[4:5], v[4:5], 1.0 op_sel_hi:[1,0] neg_lo:[1,0] neg_hi:[1,0]
	v_cmp_eq_u32_e32 vcc, 3, v27
	v_pk_mul_f32 v[4:5], v[4:5], v[6:7]
	v_pk_add_f32 v[6:7], v[8:9], 1.0 op_sel_hi:[1,0] neg_lo:[1,0] neg_hi:[1,0]
	v_cvt_pk_bf16_f32 v4, v4, v5
	v_pk_mul_f32 v[6:7], v[6:7], v[10:11]
	v_sub_f32_e32 v10, v22, v79
	v_cvt_pk_bf16_f32 v5, v6, v7
	v_sub_f32_e32 v6, v22, v73
	v_sub_f32_e32 v7, v22, v77
	v_mul_f32_e32 v6, 0x3fb8aa3b, v6
	v_mul_f32_e32 v7, 0x3fb8aa3b, v7
	v_sub_f32_e32 v11, v22, v25
	v_exp_f32_e32 v6, v6
	v_exp_f32_e32 v7, v7
	v_mul_f32_e32 v10, 0x3fb8aa3b, v10
	v_mul_f32_e32 v11, 0x3fb8aa3b, v11
	v_exp_f32_e32 v10, v10
	v_exp_f32_e32 v11, v11
	v_pk_add_f32 v[8:9], v[14:15], 1.0 op_sel_hi:[1,0] neg_lo:[1,0] neg_hi:[1,0]
	ds_write_b128 v21, v[30:33] offset:128
	v_pk_mul_f32 v[6:7], v[8:9], v[6:7]
	v_pk_add_f32 v[8:9], v[18:19], 1.0 op_sel_hi:[1,0] neg_lo:[1,0] neg_hi:[1,0]
	v_cvt_pk_bf16_f32 v6, v6, v7
	v_pk_mul_f32 v[8:9], v[8:9], v[10:11]
	s_nop 0
	v_cvt_pk_bf16_f32 v7, v8, v9
	ds_write_b128 v3, v[4:7] offset:128
	s_and_saveexec_b64 s[8:9], vcc
	s_cbranch_execz .LBB0_793
	v_mul_f32_e32 v3, 0x3fb8aa3b, v20
	v_exp_f32_e32 v4, v3
	v_mul_f32_e32 v3, 0x3fb8aa3b, v22
	v_exp_f32_e32 v5, v3
	v_ashrrev_i32_e32 v3, 31, v2
	v_readlane_b32 s22, v254, 4
	v_lshlrev_b64 v[2:3], 9, v[2:3]
	v_readlane_b32 s23, v254, 5
	v_lshlrev_b32_e32 v64, 3, v28
	s_nop 0
	v_lshl_add_u64 v[2:3], s[22:23], 0, v[2:3]
	v_lshl_add_u64 v[2:3], v[2:3], 0, v[64:65]
	global_store_dwordx2 v[2:3], v[4:5], off
	s_branch .LBB0_793

; DI unsigned pk_bf16(float lo, float hi) { f32x2_t v = {lo, hi}; return __builtin_bit_cast(unsigned, __builtin_convertvector(v, bf16x2_t)); }
; DI float bflo(unsigned u) { return __uint_as_float(u << 16); }
; DI float bfhi(unsigned u) { return __uint_as_float(u & 0xffff0000u); }
; DI float fsilu(float x) { return x * fsigmoid(x); }
; DI void h3_task(const Params& p, int c, int h, char* lds) {
;     ...
; #pragma unroll
;   for (int j = 0; j < 2; ++j) {
;     const int t = 32 * j + r;
;     const float tot = red[t] + red[64 + t] + red[128 + t] + red[192 + t];
;     const float rstd = __builtin_amdgcn_rsqf(tot * (1.0f / 128.0f) + 1e-6f);
;     const size_t row = (size_t)(c * 64 + t);
; #pragma unroll
;     for (int g4 = 0; g4 < 4; ++g4) {
;       const int v0 = h * 128 + 32 * w + 8 * g4 + 4 * hh;
;       const u32x2 gav = gaq[j][g4];
;       const f32x4 gnv = *(const f32x4*)(p.gn + v0);
;       const float o0 = ao[j][4 * g4 + 0] * rstd * gnv[0] * fsilu(bflo(gav[0]));
;       const float o1 = ao[j][4 * g4 + 1] * rstd * gnv[1] * fsilu(bfhi(gav[0]));
;       const float o2 = ao[j][4 * g4 + 2] * rstd * gnv[2] * fsilu(bflo(gav[1]));
;       const float o3 = ao[j][4 * g4 + 3] * rstd * gnv[3] * fsilu(bfhi(gav[1]));
;       u32x2 ov; ov[0] = pk_bf16(o0, o1); ov[1] = pk_bf16(o2, o3);
;       *(u32x2*)((u16*)(p.ws + OFF_OAB) + row * 1024 + v0) = ov;
.LBB0_908:
	s_or_b64 exec, exec, s[8:9]
	v_or_b32_e32 v196, v141, v139
	v_lshlrev_b32_e32 v196, 2, v196
	global_load_dwordx4 v[180:183], v196, s[68:69]
	global_load_dwordx4 v[184:187], v196, s[68:69] offset:32
	global_load_dwordx4 v[188:191], v196, s[68:69] offset:64
	global_load_dwordx4 v[192:195], v196, s[68:69] offset:96
	s_movk_i32 s2, 0xff04
	v_mad_i32_i24 v36, v140, s2, v64
	v_add_u32_e32 v34, 0x8800, v36
	s_waitcnt lgkmcnt(0)
	s_barrier
	ds_read2_b32 v[32:33], v34 offset0:128 offset1:160
	ds_read2_b32 v[34:35], v34 offset0:192 offset1:224
	v_or_b32_e32 v50, v141, v139
	v_lshlrev_b32_e32 v46, 16, v134
	v_and_b32_e32 v47, 0xffff0000, v134
	v_readlane_b32 s2, v254, 12
	s_waitcnt lgkmcnt(0)
	v_add_f32_e32 v32, v32, v34
	v_add_u32_e32 v34, 0x8c00, v36
	ds_read2_b32 v[36:37], v34 offset1:32
	ds_read2_b32 v[38:39], v34 offset0:64 offset1:96
	v_lshlrev_b32_e32 v34, 2, v50
	v_lshlrev_b64 v[44:45], 11, v[136:137]
	s_waitcnt lgkmcnt(1)
	v_add_f32_e32 v32, v32, v36
	v_mul_f32_e32 v36, 0xbfb8aa3b, v46
	v_exp_f32_e32 v36, v36
	s_waitcnt lgkmcnt(0)
	v_add_f32_e32 v32, v32, v38
	v_mov_b32_e32 v38, 0x358637bd
	v_fmamk_f32 v32, v32, 0x3c000000, v38
	v_add_f32_e32 v36, 1.0, v36
	v_rcp_f32_e32 v48, v36
	v_mul_f32_e32 v36, 0xbfb8aa3b, v47
	v_exp_f32_e32 v36, v36
	v_rsq_f32_e32 v32, v32
	v_readlane_b32 s3, v254, 13
	v_lshlrev_b32_e32 v64, 1, v50
	v_add_f32_e32 v36, 1.0, v36
	v_rcp_f32_e32 v49, v36
	v_pk_mul_f32 v[16:17], v[16:17], v[32:33] op_sel_hi:[1,0]
	v_pk_mul_f32 v[18:19], v[18:19], v[32:33] op_sel_hi:[1,0]
	v_pk_mul_f32 v[20:21], v[20:21], v[32:33] op_sel_hi:[1,0]
	v_pk_mul_f32 v[22:23], v[22:23], v[32:33] op_sel_hi:[1,0]
	v_pk_mul_f32 v[24:25], v[24:25], v[32:33] op_sel_hi:[1,0]
	v_pk_mul_f32 v[26:27], v[26:27], v[32:33] op_sel_hi:[1,0]
	s_waitcnt vmcnt(0)
	v_pk_mul_f32 v[16:17], v[180:181], v[16:17]
	v_pk_mul_f32 v[40:41], v[48:49], v[46:47]
	v_pk_mul_f32 v[18:19], v[182:183], v[18:19]
	v_pk_mul_f32 v[16:17], v[40:41], v[16:17]
	v_lshlrev_b32_e32 v40, 16, v135
	v_mul_f32_e32 v36, 0xbfb8aa3b, v40
	v_exp_f32_e32 v36, v36
	v_and_b32_e32 v41, 0xffff0000, v135
	v_add_f32_e32 v36, 1.0, v36
	v_rcp_f32_e32 v46, v36
	v_mul_f32_e32 v36, 0xbfb8aa3b, v41
	v_exp_f32_e32 v36, v36
	s_nop 0
	v_add_f32_e32 v36, 1.0, v36
	v_rcp_f32_e32 v47, v36
	s_nop 0
	v_pk_mul_f32 v[40:41], v[46:47], v[40:41]
	s_nop 0
	v_pk_mul_f32 v[18:19], v[40:41], v[18:19]
	v_cvt_pk_bf16_f32 v40, v16, v17
	v_lshl_add_u64 v[16:17], s[2:3], 0, v[44:45]
	v_cvt_pk_bf16_f32 v41, v18, v19
	v_lshl_add_u64 v[16:17], v[16:17], 0, v[64:65]
	global_store_dwordx2 v[16:17], v[40:41], off
	v_lshlrev_b32_e32 v18, 16, v132
	v_mul_f32_e32 v36, 0xbfb8aa3b, v18
	v_exp_f32_e32 v36, v36
	v_and_b32_e32 v19, 0xffff0000, v132
	v_add_f32_e32 v36, 1.0, v36
	v_rcp_f32_e32 v44, v36
	v_mul_f32_e32 v36, 0xbfb8aa3b, v19
	v_exp_f32_e32 v36, v36
	v_pk_mul_f32 v[20:21], v[184:185], v[20:21]
	v_add_f32_e32 v36, 1.0, v36
	v_rcp_f32_e32 v45, v36
	v_pk_mul_f32 v[22:23], v[186:187], v[22:23]
	v_pk_mul_f32 v[18:19], v[44:45], v[18:19]
	s_nop 0
	v_pk_mul_f32 v[18:19], v[18:19], v[20:21]
	v_lshlrev_b32_e32 v20, 16, v133
	v_mul_f32_e32 v36, 0xbfb8aa3b, v20
	v_exp_f32_e32 v36, v36
	v_and_b32_e32 v21, 0xffff0000, v133
	v_cvt_pk_bf16_f32 v18, v18, v19
	v_add_f32_e32 v36, 1.0, v36
	v_rcp_f32_e32 v40, v36
	v_mul_f32_e32 v36, 0xbfb8aa3b, v21
	v_exp_f32_e32 v36, v36
	s_nop 0
	v_add_f32_e32 v36, 1.0, v36
	v_rcp_f32_e32 v41, v36
	s_nop 0
	v_pk_mul_f32 v[20:21], v[40:41], v[20:21]
	s_nop 0
	v_pk_mul_f32 v[20:21], v[20:21], v[22:23]
	v_lshlrev_b32_e32 v22, 16, v130
	v_cvt_pk_bf16_f32 v19, v20, v21
	global_store_dwordx2 v[16:17], v[18:19], off offset:16
	v_and_b32_e32 v23, 0xffff0000, v130
	v_mul_f32_e32 v36, 0xbfb8aa3b, v22
	v_exp_f32_e32 v36, v36
	v_pk_mul_f32 v[18:19], v[24:25], v[188:189]
	v_mul_f32_e32 v24, 0xbfb8aa3b, v23
	v_exp_f32_e32 v24, v24
	v_add_f32_e32 v36, 1.0, v36
	v_rcp_f32_e32 v40, v36
	v_pk_mul_f32 v[20:21], v[26:27], v[190:191]
	v_add_f32_e32 v24, 1.0, v24
	v_rcp_f32_e32 v41, v24
	v_pk_mul_f32 v[26:27], v[28:29], v[32:33] op_sel_hi:[1,0]
	v_pk_mul_f32 v[22:23], v[40:41], v[22:23]
	s_nop 0
	v_pk_mul_f32 v[18:19], v[22:23], v[18:19]
	v_lshlrev_b32_e32 v22, 16, v131
	v_and_b32_e32 v23, 0xffff0000, v131
	v_mul_f32_e32 v24, 0xbfb8aa3b, v22
	v_mul_f32_e32 v25, 0xbfb8aa3b, v23
	v_exp_f32_e32 v24, v24
	v_exp_f32_e32 v25, v25
	v_cvt_pk_bf16_f32 v18, v18, v19
	v_add_f32_e32 v24, 1.0, v24
	v_add_f32_e32 v25, 1.0, v25
	v_rcp_f32_e32 v24, v24
	v_rcp_f32_e32 v25, v25
	s_nop 0
	v_pk_mul_f32 v[22:23], v[24:25], v[22:23]
	s_nop 0
	v_pk_mul_f32 v[20:21], v[22:23], v[20:21]
	v_lshlrev_b32_e32 v22, 16, v128
	v_cvt_pk_bf16_f32 v19, v20, v21
	global_store_dwordx2 v[16:17], v[18:19], off offset:32
	v_and_b32_e32 v23, 0xffff0000, v128
	v_mul_f32_e32 v24, 0xbfb8aa3b, v22
	v_mul_f32_e32 v25, 0xbfb8aa3b, v23
	v_exp_f32_e32 v24, v24
	v_exp_f32_e32 v25, v25
	v_add_f32_e32 v24, 1.0, v24
	v_add_f32_e32 v25, 1.0, v25
	v_rcp_f32_e32 v24, v24
	v_rcp_f32_e32 v25, v25
	v_pk_mul_f32 v[18:19], v[26:27], v[192:193]
	v_pk_mul_f32 v[22:23], v[24:25], v[22:23]
	v_pk_mul_f32 v[26:27], v[30:31], v[32:33] op_sel_hi:[1,0]
	v_pk_mul_f32 v[18:19], v[22:23], v[18:19]
	v_lshlrev_b32_e32 v22, 16, v129
	v_and_b32_e32 v23, 0xffff0000, v129
	v_mul_f32_e32 v24, 0xbfb8aa3b, v22
; DI unsigned pk_bf16(float lo, float hi) { f32x2_t v = {lo, hi}; return __builtin_bit_cast(unsigned, __builtin_convertvector(v, bf16x2_t)); }
; DI float bflo(unsigned u) { return __uint_as_float(u << 16); }
; DI float bfhi(unsigned u) { return __uint_as_float(u & 0xffff0000u); }
; DI float fsilu(float x) { return x * fsigmoid(x); }
; DI void h3_task(const Params& p, int c, int h, char* lds) {
;     ...
;   for (int j = 0; j < 2; ++j) {
;     const int t = 32 * j + r;
;     const float tot = red[t] + red[64 + t] + red[128 + t] + red[192 + t];
;     const float rstd = __builtin_amdgcn_rsqf(tot * (1.0f / 128.0f) + 1e-6f);
;     const size_t row = (size_t)(c * 64 + t);
; #pragma unroll
;     for (int g4 = 0; g4 < 4; ++g4) {
;       const int v0 = h * 128 + 32 * w + 8 * g4 + 4 * hh;
;       const u32x2 gav = gaq[j][g4];
;       const f32x4 gnv = *(const f32x4*)(p.gn + v0);
;       const float o0 = ao[j][4 * g4 + 0] * rstd * gnv[0] * fsilu(bflo(gav[0]));
;       const float o1 = ao[j][4 * g4 + 1] * rstd * gnv[1] * fsilu(bfhi(gav[0]));
;       const float o2 = ao[j][4 * g4 + 2] * rstd * gnv[2] * fsilu(bflo(gav[1]));
;       const float o3 = ao[j][4 * g4 + 3] * rstd * gnv[3] * fsilu(bfhi(gav[1]));
;       u32x2 ov; ov[0] = pk_bf16(o0, o1); ov[1] = pk_bf16(o2, o3);
;       *(u32x2*)((u16*)(p.ws + OFF_OAB) + row * 1024 + v0) = ov;
;     }
	v_mul_f32_e32 v25, 0xbfb8aa3b, v23
	v_exp_f32_e32 v24, v24
	v_exp_f32_e32 v25, v25
	v_pk_mul_f32 v[20:21], v[26:27], v[194:195]
	v_cvt_pk_bf16_f32 v18, v18, v19
	v_add_f32_e32 v24, 1.0, v24
	v_add_f32_e32 v25, 1.0, v25
	v_rcp_f32_e32 v24, v24
	v_rcp_f32_e32 v25, v25
	s_nop 0
	v_pk_mul_f32 v[22:23], v[24:25], v[22:23]
	s_nop 0
	v_pk_mul_f32 v[20:21], v[22:23], v[20:21]
	v_lshlrev_b32_e32 v24, 16, v124
	v_cvt_pk_bf16_f32 v19, v20, v21
	global_store_dwordx2 v[16:17], v[18:19], off offset:48
	v_or3_b32 v18, v140, v126, 32
	v_ashrrev_i32_e32 v19, 31, v18
	v_lshlrev_b64 v[22:23], 11, v[18:19]
	v_add_f32_e32 v16, v33, v35
	v_add_f32_e32 v16, v16, v37
	v_add_f32_e32 v16, v16, v39
	v_mul_f32_e32 v17, 0xbfb8aa3b, v24
	v_fmamk_f32 v16, v16, 0x3c000000, v38
	v_exp_f32_e32 v17, v17
	v_rsq_f32_e32 v16, v16
	v_and_b32_e32 v25, 0xffff0000, v124
	v_add_f32_e32 v17, 1.0, v17
	v_rcp_f32_e32 v26, v17
	v_pk_mul_f32 v[0:1], v[0:1], v[16:17] op_sel_hi:[1,0]
	v_mul_f32_e32 v17, 0xbfb8aa3b, v25
	v_exp_f32_e32 v17, v17
	v_pk_mul_f32 v[0:1], v[180:181], v[0:1]
	v_add_f32_e32 v17, 1.0, v17
	v_rcp_f32_e32 v27, v17
	s_nop 0
	v_pk_mul_f32 v[18:19], v[26:27], v[24:25]
	s_nop 0
	v_pk_mul_f32 v[0:1], v[18:19], v[0:1]
	v_lshlrev_b32_e32 v18, 16, v125
	v_mul_f32_e32 v17, 0xbfb8aa3b, v18
	v_exp_f32_e32 v17, v17
	v_and_b32_e32 v19, 0xffff0000, v125
	v_add_f32_e32 v17, 1.0, v17
	v_rcp_f32_e32 v24, v17
	v_pk_mul_f32 v[2:3], v[2:3], v[16:17] op_sel_hi:[1,0]
	v_mul_f32_e32 v17, 0xbfb8aa3b, v19
	v_exp_f32_e32 v17, v17
	v_pk_mul_f32 v[2:3], v[182:183], v[2:3]
	v_add_f32_e32 v17, 1.0, v17
	v_rcp_f32_e32 v25, v17
	s_nop 0
	v_pk_mul_f32 v[18:19], v[24:25], v[18:19]
	s_nop 0
	v_pk_mul_f32 v[2:3], v[18:19], v[2:3]
	v_cvt_pk_bf16_f32 v18, v0, v1
	v_lshl_add_u64 v[0:1], s[2:3], 0, v[22:23]
	v_cvt_pk_bf16_f32 v19, v2, v3
	v_lshl_add_u64 v[0:1], v[0:1], 0, v[64:65]
	global_store_dwordx2 v[0:1], v[18:19], off
	v_lshlrev_b32_e32 v2, 16, v122
	v_mul_f32_e32 v17, 0xbfb8aa3b, v2
	v_exp_f32_e32 v17, v17
	v_and_b32_e32 v3, 0xffff0000, v122
	v_readlane_b32 s2, v255, 7
	s_add_i32 s23, s23, s2
	v_add_f32_e32 v17, 1.0, v17
	v_rcp_f32_e32 v22, v17
	v_pk_mul_f32 v[4:5], v[4:5], v[16:17] op_sel_hi:[1,0]
	v_mul_f32_e32 v17, 0xbfb8aa3b, v3
	v_exp_f32_e32 v17, v17
	v_readlane_b32 s2, v255, 9
	s_add_i32 s22, s22, s2
	s_cmpk_gt_i32 s23, 0x1ff
	v_add_f32_e32 v17, 1.0, v17
	v_rcp_f32_e32 v23, v17
	v_readlane_b32 s3, v255, 8
	v_pk_mul_f32 v[2:3], v[22:23], v[2:3]
	v_pk_mul_f32 v[4:5], v[184:185], v[4:5]
	s_nop 0
	v_pk_mul_f32 v[2:3], v[2:3], v[4:5]
	v_lshlrev_b32_e32 v4, 16, v123
	v_mul_f32_e32 v17, 0xbfb8aa3b, v4
	v_exp_f32_e32 v17, v17
	v_and_b32_e32 v5, 0xffff0000, v123
	v_cvt_pk_bf16_f32 v2, v2, v3
	v_add_f32_e32 v17, 1.0, v17
	v_rcp_f32_e32 v18, v17
	v_pk_mul_f32 v[6:7], v[6:7], v[16:17] op_sel_hi:[1,0]
	v_mul_f32_e32 v17, 0xbfb8aa3b, v5
	v_exp_f32_e32 v17, v17
	v_pk_mul_f32 v[6:7], v[186:187], v[6:7]
	v_add_f32_e32 v17, 1.0, v17
	v_rcp_f32_e32 v19, v17
	s_nop 0
	v_pk_mul_f32 v[4:5], v[18:19], v[4:5]
	s_nop 0
	v_pk_mul_f32 v[4:5], v[4:5], v[6:7]
	v_lshlrev_b32_e32 v6, 16, v120
	v_cvt_pk_bf16_f32 v3, v4, v5
	global_store_dwordx2 v[0:1], v[2:3], off offset:16
	v_mul_f32_e32 v17, 0xbfb8aa3b, v6
	v_exp_f32_e32 v17, v17
	v_and_b32_e32 v7, 0xffff0000, v120
	v_add_f32_e32 v17, 1.0, v17
	v_pk_mul_f32 v[8:9], v[8:9], v[16:17] op_sel_hi:[1,0]
	v_rcp_f32_e32 v18, v17
	v_pk_mul_f32 v[10:11], v[10:11], v[16:17] op_sel_hi:[1,0]
	v_pk_mul_f32 v[2:3], v[8:9], v[188:189]
	v_mul_f32_e32 v8, 0xbfb8aa3b, v7
	v_exp_f32_e32 v8, v8
	v_pk_mul_f32 v[4:5], v[10:11], v[190:191]
	v_pk_mul_f32 v[10:11], v[12:13], v[16:17] op_sel_hi:[1,0]
	v_add_f32_e32 v8, 1.0, v8
	v_rcp_f32_e32 v19, v8
	s_nop 0
	v_pk_mul_f32 v[6:7], v[18:19], v[6:7]
	s_nop 0
	v_pk_mul_f32 v[2:3], v[6:7], v[2:3]
	v_lshlrev_b32_e32 v6, 16, v121
	v_and_b32_e32 v7, 0xffff0000, v121
	v_mul_f32_e32 v8, 0xbfb8aa3b, v6
	v_mul_f32_e32 v9, 0xbfb8aa3b, v7
	v_exp_f32_e32 v8, v8
	v_exp_f32_e32 v9, v9
	v_cvt_pk_bf16_f32 v2, v2, v3
	v_add_f32_e32 v8, 1.0, v8
	v_add_f32_e32 v9, 1.0, v9
	v_rcp_f32_e32 v8, v8
	v_rcp_f32_e32 v9, v9
	s_nop 0
	v_pk_mul_f32 v[6:7], v[8:9], v[6:7]
	s_nop 0
	v_pk_mul_f32 v[4:5], v[6:7], v[4:5]
	v_lshlrev_b32_e32 v6, 16, v118
	v_cvt_pk_bf16_f32 v3, v4, v5
	global_store_dwordx2 v[0:1], v[2:3], off offset:32
	v_and_b32_e32 v7, 0xffff0000, v118
	v_mul_f32_e32 v8, 0xbfb8aa3b, v6
	v_mul_f32_e32 v9, 0xbfb8aa3b, v7
	v_exp_f32_e32 v8, v8
	v_exp_f32_e32 v9, v9
	v_add_f32_e32 v8, 1.0, v8
	v_add_f32_e32 v9, 1.0, v9
	v_rcp_f32_e32 v8, v8
	v_rcp_f32_e32 v9, v9
	v_pk_mul_f32 v[2:3], v[10:11], v[192:193]
	v_pk_mul_f32 v[6:7], v[8:9], v[6:7]
	v_pk_mul_f32 v[10:11], v[14:15], v[16:17] op_sel_hi:[1,0]
	v_pk_mul_f32 v[2:3], v[6:7], v[2:3]
	v_lshlrev_b32_e32 v6, 16, v119
	v_and_b32_e32 v7, 0xffff0000, v119
	v_mul_f32_e32 v8, 0xbfb8aa3b, v6
	v_mul_f32_e32 v9, 0xbfb8aa3b, v7
	v_exp_f32_e32 v8, v8
	v_exp_f32_e32 v9, v9
	v_pk_mul_f32 v[4:5], v[10:11], v[194:195]
	v_cvt_pk_bf16_f32 v2, v2, v3
	v_add_f32_e32 v8, 1.0, v8
	v_add_f32_e32 v9, 1.0, v9
	v_rcp_f32_e32 v8, v8
	v_rcp_f32_e32 v9, v9
	s_nop 0
	v_pk_mul_f32 v[6:7], v[8:9], v[6:7]
	s_nop 0
	v_pk_mul_f32 v[4:5], v[6:7], v[4:5]
	s_nop 0
	v_cvt_pk_bf16_f32 v3, v4, v5
	global_store_dwordx2 v[0:1], v[2:3], off offset:48
	s_barrier
	s_cbranch_scc1 .LBB0_915

; __global__ void __launch_bounds__(512, 2) fwd_megakernel(Params p) {
;   extern __shared__ __attribute__((aligned(16))) char lds[];
	.amdhsa_kernel _Z14fwd_megakernel6Params
		.amdhsa_group_segment_fixed_size 0
		.amdhsa_private_segment_fixed_size 0
		.amdhsa_kernarg_size 416
		.amdhsa_user_sgpr_count 2
		.amdhsa_user_sgpr_dispatch_ptr 0
		.amdhsa_user_sgpr_queue_ptr 0
		.amdhsa_user_sgpr_kernarg_segment_ptr 1
		.amdhsa_user_sgpr_dispatch_id 0
		.amdhsa_user_sgpr_kernarg_preload_length 0
		.amdhsa_user_sgpr_kernarg_preload_offset 0
		.amdhsa_user_sgpr_private_segment_size 0
		.amdhsa_uses_dynamic_stack 0
		.amdhsa_enable_private_segment 0
		.amdhsa_system_sgpr_workgroup_id_x 1
		.amdhsa_system_sgpr_workgroup_id_y 0
		.amdhsa_system_sgpr_workgroup_id_z 0
		.amdhsa_system_sgpr_workgroup_info 0
		.amdhsa_system_vgpr_workitem_id 2
		.amdhsa_next_free_vgpr 256
		.amdhsa_next_free_sgpr 102
		.amdhsa_accum_offset 256
		.amdhsa_reserve_vcc 1
		.amdhsa_float_round_mode_32 0
		.amdhsa_float_round_mode_16_64 0
		.amdhsa_float_denorm_mode_32 3
		.amdhsa_float_denorm_mode_16_64 3
		.amdhsa_dx10_clamp 1
		.amdhsa_ieee_mode 1
		.amdhsa_fp16_overflow 0
		.amdhsa_tg_split 0
		.amdhsa_exception_fp_ieee_invalid_op 0
		.amdhsa_exception_fp_denorm_src 0
		.amdhsa_exception_fp_ieee_div_zero 0
		.amdhsa_exception_fp_ieee_overflow 0
		.amdhsa_exception_fp_ieee_underflow 0
		.amdhsa_exception_fp_ieee_inexact 0
		.amdhsa_exception_int_div_zero 0
	.end_amdhsa_kernel
